# FFN1 GEMM: accumulator zeroing (99 VALU moves per unit) replaced by C=0 on the first K-iteration's k=0 MFMAs
# speedup vs baseline: 1.0019x; 1.0019x over previous
; __device__ __forceinline__ int otid(int wv) { int ln; asm volatile("v_mbcnt_lo_u32_b32 %0, -1, 0\n\tv_mbcnt_hi_u32_b32 %0, -1, %0" : "=v"(ln)); return wv * 64 + ln; }
; template <class Epi, class Sched>
; __device__ __forceinline__ void gemm_phase(int wv, LAS unsigned char* lds, const int K, const Sched& S, const Epi& E) {
;     ...
;         { const int t2 = otid(wv); E(acc, cur, wr, wc, t2 & 15, (t2 >> 4) & 3); }
;         if (!has_next) break;
; #pragma unroll
;         for (int a = 0; a < 2; ++a)
; #pragma unroll
;             for (int b = 0; b < 2; ++b)
; #pragma unroll
;                 for (int m = 0; m < 4; ++m)
; #pragma unroll
;                     for (int n = 0; n < 2; ++n) acc[a][b][m][n] = (f32x4){0.f, 0.f, 0.f, 0.f};
;         cur = nxt; cA = nA; cB = nB; ++ui;
.LBB0_1315:
	s_cmp_eq_u32 s34, 0
	s_cselect_b64 s[34:35], -1, 0
	s_add_u32 s36, s36, 0x40080
	s_addc_u32 s37, s37, 0
	s_add_u32 s4, s38, 0x100
	s_addc_u32 s5, s39, 0
	s_mov_b32 s75, -2
	s_branch .LBB0_1317

; #define G8_STAGE(bufoff, gbase, voff) do { _Pragma("unroll") for (int _i = 0; _i < 2; ++_i) \
;         __builtin_amdgcn_global_load_lds((const unsigned*)((const char*)(gbase) + (voff)[_i]), (LAS unsigned*)(lds + (bufoff) + ldsw + _i * 8192), 16, 0, 0); } while (0)
; #define G8_LDA(dst, b, h) do { _Pragma("unroll") for (int m = 0; m < 4; ++m) _Pragma("unroll") for (int k = 0; k < 2; ++k) dst[m][k] = *(const LAS bf16x8*)(lds + G8_SA(b, h) + aoff + m * 2048 + k * 1024); } while (0)
; #define G8_LDB(dst, b, h) do { _Pragma("unroll") for (int n = 0; n < 2; ++n) _Pragma("unroll") for (int k = 0; k < 2; ++k) dst[n][k] = *(const LAS bf16x8*)(lds + G8_SB(b, h) + boff + n * 2048 + k * 1024); } while (0)
; #define G8_MMA(ai, bj, At, Bt) do { __builtin_amdgcn_s_setprio(1); _Pragma("unroll") for (int m = 0; m < 4; ++m) _Pragma("unroll") for (int n = 0; n < 2; ++n) _Pragma("unroll") for (int k = 0; k < 2; ++k) \
;         acc[ai][bj][m][n] = __builtin_amdgcn_mfma_f32_16x16x32_bf16(Bt[n][k], At[m][k], acc[ai][bj][m][n], 0, 0, 0); __builtin_amdgcn_s_setprio(0); } while (0)
; #define G8_WAIT_V(n) asm volatile("s_waitcnt vmcnt(" #n ")" ::: "memory")
; #define G8_WAIT_L(n) asm volatile("s_waitcnt lgkmcnt(" #n ")" ::: "memory")
; template <class Epi, class Sched>
; __device__ __forceinline__ void gemm_phase(int wv, LAS unsigned char* lds, const int K, const Sched& S, const Epi& E) {
;     ...
;         for (int t = 0; t < nt; t += 2) {
;             const bool last = (t == nt - 2);
;             const char* a1 = cA + (size_t)(t + 1) * kstep;
;             const char* a2 = last ? nA : cA + (size_t)(t + 2) * kstep; const char* b2 = last ? nB : cB + (size_t)(t + 2) * kstep;
;             const char* a3 = a2 + kstep; const char* b3 = b2 + kstep;
;             G8_LDB(B0, 0, 0); G8_SCHED; G8_LDA(At, 0, 0); G8_STAGE(G8_SA(1, 1), a1 + hstep, voffA);
;             G8_WAIT_L(8); G8_BAR; G8_WAIT_L(0); G8_MMA(0, 0, At, B0); G8_BAR; G8_SCHED;
;             G8_LDB(B1, 0, 1); G8_STAGE(G8_SB(0, 0), b2, voffB);
;             G8_BAR; G8_WAIT_L(0); G8_MMA(0, 1, At, B1); G8_BAR;
;             if (full) G8_LDA(At, 0, 1); G8_STAGE(G8_SA(0, 0), a2, voffA);
;             G8_BAR; G8_WAIT_L(0); if (full) G8_MMA(1, 0, At, B0); G8_BAR; G8_SCHED;
;             G8_STAGE(G8_SB(0, 1), b2 + hstep, voffB);
;             G8_WAIT_V(6); G8_BAR; if (full) G8_MMA(1, 1, At, B1); G8_BAR;
.LBB0_1317:
	s_add_i32 s76, 0, 0x10000
	v_add_u32_e32 v0, s76, v220
	ds_read_b128 v[180:183], v0
	ds_read_b128 v[184:187], v0 offset:1024
	ds_read_b128 v[188:191], v0 offset:2048
	ds_read_b128 v[192:195], v0 offset:3072
	s_cmp_eq_u32 s75, 12
	s_cselect_b64 s[40:41], -1, 0
	s_and_b64 s[14:15], s[40:41], exec
	s_cselect_b32 s39, s29, s5
	s_cselect_b32 s38, s28, s4
	v_lshl_add_u64 v[2:3], s[36:37], 0, v[210:211]
	s_add_i32 m0, s42, 0xc000
	s_waitcnt lgkmcnt(0)
	ds_read_b128 v[144:147], v221
	ds_read_b128 v[160:163], v221 offset:1024
	ds_read_b128 v[140:143], v221 offset:2048
	ds_read_b128 v[156:159], v221 offset:3072
	ds_read_b128 v[136:139], v221 offset:4096
	ds_read_b128 v[152:155], v221 offset:5120
	ds_read_b128 v[132:135], v221 offset:6144
	ds_read_b128 v[148:151], v221 offset:7168
	global_load_lds_dwordx4 v[2:3], off
	v_lshl_add_u64 v[2:3], s[36:37], 0, v[212:213]
	s_add_i32 m0, s42, 0xe000
	s_nop 0
	global_load_lds_dwordx4 v[2:3], off
	s_waitcnt lgkmcnt(8)
	s_barrier
	s_waitcnt lgkmcnt(0)
	s_setprio 1
	s_waitcnt lgkmcnt(0)
	s_cmp_eq_i32 s75, -2
	s_cbranch_scc1 .Lzk8_g0
	v_mfma_f32_16x16x32_bf16 v[124:127], v[180:183], v[144:147], v[124:127]
	v_mfma_f32_16x16x32_bf16 v[128:131], v[188:191], v[144:147], v[128:131]
	v_mfma_f32_16x16x32_bf16 v[108:111], v[180:183], v[140:143], v[108:111]
	v_mfma_f32_16x16x32_bf16 v[112:115], v[188:191], v[140:143], v[112:115]
	v_mfma_f32_16x16x32_bf16 v[92:95], v[180:183], v[136:139], v[92:95]
	v_mfma_f32_16x16x32_bf16 v[96:99], v[188:191], v[136:139], v[96:99]
	v_mfma_f32_16x16x32_bf16 v[76:79], v[180:183], v[132:135], v[76:79]
	v_mfma_f32_16x16x32_bf16 v[80:83], v[188:191], v[132:135], v[80:83]
	v_mfma_f32_16x16x32_bf16 v[124:127], v[184:187], v[160:163], v[124:127]
	v_mfma_f32_16x16x32_bf16 v[128:131], v[192:195], v[160:163], v[128:131]
	v_mfma_f32_16x16x32_bf16 v[108:111], v[184:187], v[156:159], v[108:111]
	v_mfma_f32_16x16x32_bf16 v[112:115], v[192:195], v[156:159], v[112:115]
	v_mfma_f32_16x16x32_bf16 v[92:95], v[184:187], v[152:155], v[92:95]
	v_mfma_f32_16x16x32_bf16 v[96:99], v[192:195], v[152:155], v[96:99]
	v_mfma_f32_16x16x32_bf16 v[76:79], v[184:187], v[148:151], v[76:79]
	v_mfma_f32_16x16x32_bf16 v[80:83], v[192:195], v[148:151], v[80:83]
.Lzk8_b0:
	s_setprio 0
	s_barrier
	v_add_u32_e32 v0, 0, v220
	v_add_u32_e32 v2, 0x14000, v0
	s_add_i32 s14, s76, s3
	ds_read_b128 v[164:167], v2
	ds_read_b128 v[168:171], v2 offset:1024
	ds_read_b128 v[172:175], v2 offset:2048
	ds_read_b128 v[176:179], v2 offset:3072
	v_lshl_add_u64 v[2:3], s[38:39], 0, v[206:207]
	s_mov_b32 m0, s14
	v_lshl_add_u64 v[214:215], s[38:39], 0, v[208:209]
	global_load_lds_dwordx4 v[2:3], off
	s_add_i32 m0, s14, 0x2000
	s_nop 0
	global_load_lds_dwordx4 v[214:215], off
	s_barrier
	s_waitcnt lgkmcnt(0)
	s_setprio 1
	s_waitcnt lgkmcnt(0)
	s_cmp_eq_i32 s75, -2
	s_cbranch_scc1 .Lzk8_g1
	v_mfma_f32_16x16x32_bf16 v[116:119], v[164:167], v[144:147], v[116:119]
	v_mfma_f32_16x16x32_bf16 v[120:123], v[172:175], v[144:147], v[120:123]
	v_mfma_f32_16x16x32_bf16 v[100:103], v[164:167], v[140:143], v[100:103]
	v_mfma_f32_16x16x32_bf16 v[104:107], v[172:175], v[140:143], v[104:107]
	v_mfma_f32_16x16x32_bf16 v[84:87], v[164:167], v[136:139], v[84:87]
	v_mfma_f32_16x16x32_bf16 v[88:91], v[172:175], v[136:139], v[88:91]
	v_mfma_f32_16x16x32_bf16 v[72:75], v[164:167], v[132:135], v[72:75]
	v_mfma_f32_16x16x32_bf16 v[68:71], v[172:175], v[132:135], v[68:71]
	v_mfma_f32_16x16x32_bf16 v[116:119], v[168:171], v[160:163], v[116:119]
	v_mfma_f32_16x16x32_bf16 v[120:123], v[176:179], v[160:163], v[120:123]
	v_mfma_f32_16x16x32_bf16 v[100:103], v[168:171], v[156:159], v[100:103]
	v_mfma_f32_16x16x32_bf16 v[104:107], v[176:179], v[156:159], v[104:107]
	v_mfma_f32_16x16x32_bf16 v[84:87], v[168:171], v[152:155], v[84:87]
	v_mfma_f32_16x16x32_bf16 v[88:91], v[176:179], v[152:155], v[88:91]
	v_mfma_f32_16x16x32_bf16 v[72:75], v[168:171], v[148:151], v[72:75]
	v_mfma_f32_16x16x32_bf16 v[68:71], v[176:179], v[148:151], v[68:71]
.Lzk8_b1:
	s_setprio 0
	v_cndmask_b32_e64 v198, 0, 1, s[34:35]
	v_cmp_ne_u32_e64 s[14:15], 1, v198
	s_andn2_b64 vcc, exec, s[34:35]
	s_barrier
	s_cbranch_vccnz .LBB0_1319
	ds_read_b128 v[144:147], v221 offset:16384
	ds_read_b128 v[160:163], v221 offset:17408
	ds_read_b128 v[140:143], v221 offset:18432
	ds_read_b128 v[156:159], v221 offset:19456
	ds_read_b128 v[136:139], v221 offset:20480
	ds_read_b128 v[152:155], v221 offset:21504
	ds_read_b128 v[132:135], v221 offset:22528
	ds_read_b128 v[148:151], v221 offset:23552
.LBB0_1319:
	s_add_u32 s76, s36, 0xfffc0080
	s_addc_u32 s77, s37, -1
	s_and_b64 s[40:41], s[40:41], exec
	s_cselect_b32 s41, s27, s77
	s_cselect_b32 s40, s26, s76
	s_mov_b32 m0, s42
	v_lshl_add_u64 v[216:217], s[40:41], 0, v[206:207]
	global_load_lds_dwordx4 v[216:217], off
	v_lshl_add_u64 v[218:219], s[40:41], 0, v[208:209]
	s_mov_b32 m0, s43
	s_and_b64 vcc, exec, s[14:15]
	global_load_lds_dwordx4 v[218:219], off
	s_barrier
	s_waitcnt lgkmcnt(0)
	s_cbranch_vccnz .LBB0_1321
	s_setprio 1
	s_waitcnt lgkmcnt(0)
	s_cmp_eq_i32 s75, -2
	s_cbranch_scc1 .Lzk8_g2
	v_mfma_f32_16x16x32_bf16 v[60:63], v[180:183], v[144:147], v[60:63]
	v_mfma_f32_16x16x32_bf16 v[64:67], v[188:191], v[144:147], v[64:67]
	v_mfma_f32_16x16x32_bf16 v[44:47], v[180:183], v[140:143], v[44:47]
	v_mfma_f32_16x16x32_bf16 v[48:51], v[188:191], v[140:143], v[48:51]
	v_mfma_f32_16x16x32_bf16 v[28:31], v[180:183], v[136:139], v[28:31]
	v_mfma_f32_16x16x32_bf16 v[32:35], v[188:191], v[136:139], v[32:35]
	v_mfma_f32_16x16x32_bf16 v[12:15], v[180:183], v[132:135], v[12:15]
	v_mfma_f32_16x16x32_bf16 v[16:19], v[188:191], v[132:135], v[16:19]
	v_mfma_f32_16x16x32_bf16 v[60:63], v[184:187], v[160:163], v[60:63]
	v_mfma_f32_16x16x32_bf16 v[64:67], v[192:195], v[160:163], v[64:67]
	v_mfma_f32_16x16x32_bf16 v[44:47], v[184:187], v[156:159], v[44:47]
	v_mfma_f32_16x16x32_bf16 v[48:51], v[192:195], v[156:159], v[48:51]
	v_mfma_f32_16x16x32_bf16 v[28:31], v[184:187], v[152:155], v[28:31]
	v_mfma_f32_16x16x32_bf16 v[32:35], v[192:195], v[152:155], v[32:35]
	v_mfma_f32_16x16x32_bf16 v[12:15], v[184:187], v[148:151], v[12:15]
	v_mfma_f32_16x16x32_bf16 v[16:19], v[192:195], v[148:151], v[16:19]
.Lzk8_b2:
	s_setprio 0
.LBB0_1321:
	s_barrier
	s_add_u32 s76, s38, 0x40000
	s_addc_u32 s77, s39, 0
	s_mov_b32 m0, s46
	v_lshl_add_u64 v[180:181], s[76:77], 0, v[206:207]
	global_load_lds_dwordx4 v[180:181], off
	v_lshl_add_u64 v[180:181], s[76:77], 0, v[208:209]
	s_mov_b32 m0, s47
	s_and_b64 vcc, exec, s[14:15]
	global_load_lds_dwordx4 v[180:181], off
	s_cmp_eq_u32 s101, 1
	s_cbranch_scc1 .Lp8rx_a
	s_waitcnt vmcnt(6)
	s_branch .Lp8rx_b

; #define G8_STAGE(bufoff, gbase, voff) do { _Pragma("unroll") for (int _i = 0; _i < 2; ++_i) \
;         __builtin_amdgcn_global_load_lds((const unsigned*)((const char*)(gbase) + (voff)[_i]), (LAS unsigned*)(lds + (bufoff) + ldsw + _i * 8192), 16, 0, 0); } while (0)
; #define G8_LDA(dst, b, h) do { _Pragma("unroll") for (int m = 0; m < 4; ++m) _Pragma("unroll") for (int k = 0; k < 2; ++k) dst[m][k] = *(const LAS bf16x8*)(lds + G8_SA(b, h) + aoff + m * 2048 + k * 1024); } while (0)
; #define G8_LDB(dst, b, h) do { _Pragma("unroll") for (int n = 0; n < 2; ++n) _Pragma("unroll") for (int k = 0; k < 2; ++k) dst[n][k] = *(const LAS bf16x8*)(lds + G8_SB(b, h) + boff + n * 2048 + k * 1024); } while (0)
; #define G8_MMA(ai, bj, At, Bt) do { __builtin_amdgcn_s_setprio(1); _Pragma("unroll") for (int m = 0; m < 4; ++m) _Pragma("unroll") for (int n = 0; n < 2; ++n) _Pragma("unroll") for (int k = 0; k < 2; ++k) \
;         acc[ai][bj][m][n] = __builtin_amdgcn_mfma_f32_16x16x32_bf16(Bt[n][k], At[m][k], acc[ai][bj][m][n], 0, 0, 0); __builtin_amdgcn_s_setprio(0); } while (0)
; #define G8_WAIT_V(n) asm volatile("s_waitcnt vmcnt(" #n ")" ::: "memory")
; #define G8_WAIT_L(n) asm volatile("s_waitcnt lgkmcnt(" #n ")" ::: "memory")
; #define G8_BAR __builtin_amdgcn_s_barrier()
; #define G8_SCHED __builtin_amdgcn_sched_barrier(0)
; template <class Epi, class Sched>
; __device__ __forceinline__ void gemm_phase(int wv, LAS unsigned char* lds, const int K, const Sched& S, const Epi& E) {
;     ...
;             G8_WAIT_V(6); G8_BAR; if (full) G8_MMA(1, 1, At, B1); G8_BAR;
;             G8_LDB(B0, 1, 0); G8_SCHED; G8_LDA(At, 1, 0); G8_STAGE(G8_SA(0, 1), a2 + hstep, voffA);
;             G8_WAIT_L(8); G8_BAR; G8_WAIT_L(0); G8_MMA(0, 0, At, B0); G8_BAR; G8_SCHED;
;             G8_LDB(B1, 1, 1); G8_STAGE(G8_SB(1, 0), b3, voffB);
;             G8_BAR; G8_WAIT_L(0); G8_MMA(0, 1, At, B1); G8_BAR;
;             if (full) G8_LDA(At, 1, 1); G8_STAGE(G8_SA(1, 0), a3, voffA);
;             G8_BAR; G8_WAIT_L(0); if (full) G8_MMA(1, 0, At, B0); G8_BAR; G8_SCHED;
;             G8_STAGE(G8_SB(1, 1), b3 + hstep, voffB);
;             G8_WAIT_V(6); G8_BAR; if (full) G8_MMA(1, 1, At, B1); G8_BAR;
.Lp8rx_b:
	s_barrier
	s_cbranch_vccnz .LBB0_1323
	s_setprio 1
	s_waitcnt lgkmcnt(0)
	s_cmp_eq_i32 s75, -2
	s_cbranch_scc1 .Lzk8_g3
	v_mfma_f32_16x16x32_bf16 v[52:55], v[164:167], v[144:147], v[52:55]
	v_mfma_f32_16x16x32_bf16 v[56:59], v[172:175], v[144:147], v[56:59]
	v_mfma_f32_16x16x32_bf16 v[36:39], v[164:167], v[140:143], v[36:39]
	v_mfma_f32_16x16x32_bf16 v[40:43], v[172:175], v[140:143], v[40:43]
	v_mfma_f32_16x16x32_bf16 v[20:23], v[164:167], v[136:139], v[20:23]
	v_mfma_f32_16x16x32_bf16 v[24:27], v[172:175], v[136:139], v[24:27]
	v_mfma_f32_16x16x32_bf16 v[4:7], v[164:167], v[132:135], v[4:7]
	v_mfma_f32_16x16x32_bf16 v[8:11], v[172:175], v[132:135], v[8:11]
	v_mfma_f32_16x16x32_bf16 v[52:55], v[168:171], v[160:163], v[52:55]
	v_mfma_f32_16x16x32_bf16 v[56:59], v[176:179], v[160:163], v[56:59]
	v_mfma_f32_16x16x32_bf16 v[36:39], v[168:171], v[156:159], v[36:39]
	v_mfma_f32_16x16x32_bf16 v[40:43], v[176:179], v[156:159], v[40:43]
	v_mfma_f32_16x16x32_bf16 v[20:23], v[168:171], v[152:155], v[20:23]
	v_mfma_f32_16x16x32_bf16 v[24:27], v[176:179], v[152:155], v[24:27]
	v_mfma_f32_16x16x32_bf16 v[4:7], v[168:171], v[148:151], v[4:7]
	v_mfma_f32_16x16x32_bf16 v[8:11], v[176:179], v[148:151], v[8:11]
.Lzk8_b3:
	s_setprio 0
.LBB0_1323:
	s_add_i32 s76, 0, 0x18000
	s_waitcnt lgkmcnt(0)
	v_add_u32_e32 v132, s76, v220
	s_barrier
	ds_read_b128 v[180:183], v132
	ds_read_b128 v[184:187], v132 offset:1024
	ds_read_b128 v[188:191], v132 offset:2048
	ds_read_b128 v[192:195], v132 offset:3072
	s_add_u32 s40, s40, 0x40000
	s_addc_u32 s41, s41, 0
	s_mov_b32 m0, s48
	v_lshl_add_u64 v[164:165], s[40:41], 0, v[206:207]
	ds_read_b128 v[144:147], v221 offset:32768
	ds_read_b128 v[160:163], v221 offset:33792
	ds_read_b128 v[140:143], v221 offset:34816
	ds_read_b128 v[156:159], v221 offset:35840
	ds_read_b128 v[136:139], v221 offset:36864
	ds_read_b128 v[152:155], v221 offset:37888
	ds_read_b128 v[132:135], v221 offset:38912
	ds_read_b128 v[148:151], v221 offset:39936
	global_load_lds_dwordx4 v[164:165], off
	v_lshl_add_u64 v[164:165], s[40:41], 0, v[208:209]
	s_mov_b32 m0, s49
	s_nop 0
	global_load_lds_dwordx4 v[164:165], off
	s_waitcnt lgkmcnt(8)
	s_barrier
	s_waitcnt lgkmcnt(0)
	s_setprio 1
	s_waitcnt lgkmcnt(0)
	v_mfma_f32_16x16x32_bf16 v[124:127], v[180:183], v[144:147], v[124:127]
	v_mfma_f32_16x16x32_bf16 v[128:131], v[188:191], v[144:147], v[128:131]
	v_mfma_f32_16x16x32_bf16 v[108:111], v[180:183], v[140:143], v[108:111]
	v_mfma_f32_16x16x32_bf16 v[112:115], v[188:191], v[140:143], v[112:115]
	v_mfma_f32_16x16x32_bf16 v[92:95], v[180:183], v[136:139], v[92:95]
	v_mfma_f32_16x16x32_bf16 v[96:99], v[188:191], v[136:139], v[96:99]
	v_mfma_f32_16x16x32_bf16 v[76:79], v[180:183], v[132:135], v[76:79]
	v_mfma_f32_16x16x32_bf16 v[80:83], v[188:191], v[132:135], v[80:83]
	v_mfma_f32_16x16x32_bf16 v[124:127], v[184:187], v[160:163], v[124:127]
	v_mfma_f32_16x16x32_bf16 v[128:131], v[192:195], v[160:163], v[128:131]
	v_mfma_f32_16x16x32_bf16 v[108:111], v[184:187], v[156:159], v[108:111]
	v_mfma_f32_16x16x32_bf16 v[112:115], v[192:195], v[156:159], v[112:115]
	v_mfma_f32_16x16x32_bf16 v[92:95], v[184:187], v[152:155], v[92:95]
	v_mfma_f32_16x16x32_bf16 v[96:99], v[192:195], v[152:155], v[96:99]
	v_mfma_f32_16x16x32_bf16 v[76:79], v[184:187], v[148:151], v[76:79]
	v_mfma_f32_16x16x32_bf16 v[80:83], v[192:195], v[148:151], v[80:83]
	s_setprio 0
	s_barrier
	s_add_i32 s40, s76, s3
	v_add_u32_e32 v0, 0x1c000, v0
	v_lshl_add_u64 v[2:3], v[2:3], 0, s[58:59]
	s_mov_b32 m0, s40
	ds_read_b128 v[164:167], v0
	ds_read_b128 v[168:171], v0 offset:1024
	ds_read_b128 v[172:175], v0 offset:2048
	ds_read_b128 v[176:179], v0 offset:3072
	global_load_lds_dwordx4 v[2:3], off
	v_lshl_add_u64 v[2:3], v[214:215], 0, s[58:59]
	s_add_i32 m0, s40, 0x2000
	s_nop 0
	global_load_lds_dwordx4 v[2:3], off
	s_barrier
	s_waitcnt lgkmcnt(0)
	s_setprio 1
	s_waitcnt lgkmcnt(0)
	v_mfma_f32_16x16x32_bf16 v[116:119], v[164:167], v[144:147], v[116:119]
	v_mfma_f32_16x16x32_bf16 v[120:123], v[172:175], v[144:147], v[120:123]
	v_mfma_f32_16x16x32_bf16 v[100:103], v[164:167], v[140:143], v[100:103]
	v_mfma_f32_16x16x32_bf16 v[104:107], v[172:175], v[140:143], v[104:107]
	v_mfma_f32_16x16x32_bf16 v[84:87], v[164:167], v[136:139], v[84:87]
	v_mfma_f32_16x16x32_bf16 v[88:91], v[172:175], v[136:139], v[88:91]
	v_mfma_f32_16x16x32_bf16 v[72:75], v[164:167], v[132:135], v[72:75]
	v_mfma_f32_16x16x32_bf16 v[68:71], v[172:175], v[132:135], v[68:71]
	v_mfma_f32_16x16x32_bf16 v[116:119], v[168:171], v[160:163], v[116:119]
	v_mfma_f32_16x16x32_bf16 v[120:123], v[176:179], v[160:163], v[120:123]
	v_mfma_f32_16x16x32_bf16 v[100:103], v[168:171], v[156:159], v[100:103]
	v_mfma_f32_16x16x32_bf16 v[104:107], v[176:179], v[156:159], v[104:107]
	v_mfma_f32_16x16x32_bf16 v[84:87], v[168:171], v[152:155], v[84:87]
	v_mfma_f32_16x16x32_bf16 v[88:91], v[176:179], v[152:155], v[88:91]
	v_mfma_f32_16x16x32_bf16 v[72:75], v[168:171], v[148:151], v[72:75]
	v_mfma_f32_16x16x32_bf16 v[68:71], v[176:179], v[148:151], v[68:71]
	s_setprio 0
	s_cmp_eq_u32 s101, 1
	s_cbranch_scc0 .Lp8rx_c
	s_waitcnt vmcnt(10)

; #define G8_STAGE(bufoff, gbase, voff) do { _Pragma("unroll") for (int _i = 0; _i < 2; ++_i) \
;         __builtin_amdgcn_global_load_lds((const unsigned*)((const char*)(gbase) + (voff)[_i]), (LAS unsigned*)(lds + (bufoff) + ldsw + _i * 8192), 16, 0, 0); } while (0)
; #define G8_LDA(dst, b, h) do { _Pragma("unroll") for (int m = 0; m < 4; ++m) _Pragma("unroll") for (int k = 0; k < 2; ++k) dst[m][k] = *(const LAS bf16x8*)(lds + G8_SA(b, h) + aoff + m * 2048 + k * 1024); } while (0)
; #define G8_LDB(dst, b, h) do { _Pragma("unroll") for (int n = 0; n < 2; ++n) _Pragma("unroll") for (int k = 0; k < 2; ++k) dst[n][k] = *(const LAS bf16x8*)(lds + G8_SB(b, h) + boff + n * 2048 + k * 1024); } while (0)
; #define G8_MMA(ai, bj, At, Bt) do { __builtin_amdgcn_s_setprio(1); _Pragma("unroll") for (int m = 0; m < 4; ++m) _Pragma("unroll") for (int n = 0; n < 2; ++n) _Pragma("unroll") for (int k = 0; k < 2; ++k) \
;         acc[ai][bj][m][n] = __builtin_amdgcn_mfma_f32_16x16x32_bf16(Bt[n][k], At[m][k], acc[ai][bj][m][n], 0, 0, 0); __builtin_amdgcn_s_setprio(0); } while (0)
; #define G8_WAIT_V(n) asm volatile("s_waitcnt vmcnt(" #n ")" ::: "memory")
; #define G8_WAIT_L(n) asm volatile("s_waitcnt lgkmcnt(" #n ")" ::: "memory")
; #define G8_BAR __builtin_amdgcn_s_barrier()
; #define G8_SCHED __builtin_amdgcn_sched_barrier(0)
; template <class Epi, class Sched>
; __device__ __forceinline__ void gemm_phase(int wv, LAS unsigned char* lds, const int K, const Sched& S, const Epi& E) {
;     ...
;             G8_WAIT_L(8); G8_BAR; G8_WAIT_L(0); G8_MMA(0, 0, At, B0); G8_BAR; G8_SCHED;
;             G8_LDB(B1, 0, 1); G8_STAGE(G8_SB(0, 0), b2, voffB);
;             G8_BAR; G8_WAIT_L(0); G8_MMA(0, 1, At, B1); G8_BAR;
;             if (full) G8_LDA(At, 0, 1); G8_STAGE(G8_SA(0, 0), a2, voffA);
;             G8_BAR; G8_WAIT_L(0); if (full) G8_MMA(1, 0, At, B0); G8_BAR; G8_SCHED;
;             G8_STAGE(G8_SB(0, 1), b2 + hstep, voffB);
;             G8_WAIT_V(6); G8_BAR; if (full) G8_MMA(1, 1, At, B1); G8_BAR;
.Lzk8_g0:
	v_mfma_f32_16x16x32_bf16 v[124:127], v[180:183], v[144:147], 0
	v_mfma_f32_16x16x32_bf16 v[128:131], v[188:191], v[144:147], 0
	v_mfma_f32_16x16x32_bf16 v[108:111], v[180:183], v[140:143], 0
	v_mfma_f32_16x16x32_bf16 v[112:115], v[188:191], v[140:143], 0
	v_mfma_f32_16x16x32_bf16 v[92:95], v[180:183], v[136:139], 0
	v_mfma_f32_16x16x32_bf16 v[96:99], v[188:191], v[136:139], 0
	v_mfma_f32_16x16x32_bf16 v[76:79], v[180:183], v[132:135], 0
	v_mfma_f32_16x16x32_bf16 v[80:83], v[188:191], v[132:135], 0
	v_mfma_f32_16x16x32_bf16 v[124:127], v[184:187], v[160:163], v[124:127]
	v_mfma_f32_16x16x32_bf16 v[128:131], v[192:195], v[160:163], v[128:131]
	v_mfma_f32_16x16x32_bf16 v[108:111], v[184:187], v[156:159], v[108:111]
	v_mfma_f32_16x16x32_bf16 v[112:115], v[192:195], v[156:159], v[112:115]
	v_mfma_f32_16x16x32_bf16 v[92:95], v[184:187], v[152:155], v[92:95]
	v_mfma_f32_16x16x32_bf16 v[96:99], v[192:195], v[152:155], v[96:99]
	v_mfma_f32_16x16x32_bf16 v[76:79], v[184:187], v[148:151], v[76:79]
	v_mfma_f32_16x16x32_bf16 v[80:83], v[192:195], v[148:151], v[80:83]
	s_branch .Lzk8_b0
.Lzk8_g1:
	v_mfma_f32_16x16x32_bf16 v[116:119], v[164:167], v[144:147], 0
	v_mfma_f32_16x16x32_bf16 v[120:123], v[172:175], v[144:147], 0
	v_mfma_f32_16x16x32_bf16 v[100:103], v[164:167], v[140:143], 0
	v_mfma_f32_16x16x32_bf16 v[104:107], v[172:175], v[140:143], 0
	v_mfma_f32_16x16x32_bf16 v[84:87], v[164:167], v[136:139], 0
	v_mfma_f32_16x16x32_bf16 v[88:91], v[172:175], v[136:139], 0
	v_mfma_f32_16x16x32_bf16 v[72:75], v[164:167], v[132:135], 0
	v_mfma_f32_16x16x32_bf16 v[68:71], v[172:175], v[132:135], 0
	v_mfma_f32_16x16x32_bf16 v[116:119], v[168:171], v[160:163], v[116:119]
	v_mfma_f32_16x16x32_bf16 v[120:123], v[176:179], v[160:163], v[120:123]
	v_mfma_f32_16x16x32_bf16 v[100:103], v[168:171], v[156:159], v[100:103]
	v_mfma_f32_16x16x32_bf16 v[104:107], v[176:179], v[156:159], v[104:107]
	v_mfma_f32_16x16x32_bf16 v[84:87], v[168:171], v[152:155], v[84:87]
	v_mfma_f32_16x16x32_bf16 v[88:91], v[176:179], v[152:155], v[88:91]
	v_mfma_f32_16x16x32_bf16 v[72:75], v[168:171], v[148:151], v[72:75]
	v_mfma_f32_16x16x32_bf16 v[68:71], v[176:179], v[148:151], v[68:71]
	s_branch .Lzk8_b1
.Lzk8_g2:
	v_mfma_f32_16x16x32_bf16 v[60:63], v[180:183], v[144:147], 0
	v_mfma_f32_16x16x32_bf16 v[64:67], v[188:191], v[144:147], 0
	v_mfma_f32_16x16x32_bf16 v[44:47], v[180:183], v[140:143], 0
	v_mfma_f32_16x16x32_bf16 v[48:51], v[188:191], v[140:143], 0
	v_mfma_f32_16x16x32_bf16 v[28:31], v[180:183], v[136:139], 0
	v_mfma_f32_16x16x32_bf16 v[32:35], v[188:191], v[136:139], 0
	v_mfma_f32_16x16x32_bf16 v[12:15], v[180:183], v[132:135], 0
	v_mfma_f32_16x16x32_bf16 v[16:19], v[188:191], v[132:135], 0
	v_mfma_f32_16x16x32_bf16 v[60:63], v[184:187], v[160:163], v[60:63]
	v_mfma_f32_16x16x32_bf16 v[64:67], v[192:195], v[160:163], v[64:67]
	v_mfma_f32_16x16x32_bf16 v[44:47], v[184:187], v[156:159], v[44:47]
	v_mfma_f32_16x16x32_bf16 v[48:51], v[192:195], v[156:159], v[48:51]
	v_mfma_f32_16x16x32_bf16 v[28:31], v[184:187], v[152:155], v[28:31]
	v_mfma_f32_16x16x32_bf16 v[32:35], v[192:195], v[152:155], v[32:35]
	v_mfma_f32_16x16x32_bf16 v[12:15], v[184:187], v[148:151], v[12:15]
	v_mfma_f32_16x16x32_bf16 v[16:19], v[192:195], v[148:151], v[16:19]
	s_branch .Lzk8_b2
.Lzk8_g3:
	v_mfma_f32_16x16x32_bf16 v[52:55], v[164:167], v[144:147], 0
	v_mfma_f32_16x16x32_bf16 v[56:59], v[172:175], v[144:147], 0
	v_mfma_f32_16x16x32_bf16 v[36:39], v[164:167], v[140:143], 0
	v_mfma_f32_16x16x32_bf16 v[40:43], v[172:175], v[140:143], 0
	v_mfma_f32_16x16x32_bf16 v[20:23], v[164:167], v[136:139], 0
	v_mfma_f32_16x16x32_bf16 v[24:27], v[172:175], v[136:139], 0
	v_mfma_f32_16x16x32_bf16 v[4:7], v[164:167], v[132:135], 0
	v_mfma_f32_16x16x32_bf16 v[8:11], v[172:175], v[132:135], 0
	v_mfma_f32_16x16x32_bf16 v[52:55], v[168:171], v[160:163], v[52:55]
	v_mfma_f32_16x16x32_bf16 v[56:59], v[176:179], v[160:163], v[56:59]
	v_mfma_f32_16x16x32_bf16 v[36:39], v[168:171], v[156:159], v[36:39]
	v_mfma_f32_16x16x32_bf16 v[40:43], v[176:179], v[156:159], v[40:43]
	v_mfma_f32_16x16x32_bf16 v[20:23], v[168:171], v[152:155], v[20:23]
	v_mfma_f32_16x16x32_bf16 v[24:27], v[176:179], v[152:155], v[24:27]
	v_mfma_f32_16x16x32_bf16 v[4:7], v[168:171], v[148:151], v[4:7]
	v_mfma_f32_16x16x32_bf16 v[8:11], v[176:179], v[148:151], v[8:11]
	s_branch .Lzk8_b3
